# v086 + loop counters advanced inside the PV/exp block (tail keeps only the last conversions, the sum check and the exit test)
# baseline (speedup 1.0000x reference)
; #define ALAS __attribute__((address_space(3)))
; template <int N> __device__ __forceinline__ void wait_bar() { asm volatile("s_waitcnt vmcnt(%0) lgkmcnt(0)\n\ts_barrier" :: "n"(N) : "memory"); }
; template <bool WIN> ...
;     ...
;     for (int tr = 0; tr < NT; ++tr) {
;         if (tr + 2 < NT) wait_bar<2 * NPW>(); else if (tr + 1 < NT) wait_bar<NPW>(); else wait_bar<0>();
;         if (tr + 3 < NT) AT_DMA(tr + 3);
;         const int k0 = (t_lo + tr) * 64;
;         const bool skip = WIN && (k0 > qw + 31 + 128 || k0 + 63 < qw - 128);
;         if (!skip) {
;             const bool near = WIN || ((k0 - (qw + 31)) < 128 && (qw - (k0 + 63)) < 128);
;             const float cinit = near ? 0.f : (k0 > qw ? cfar_hi : cfar_lo);
;     ...
;             float ls0 = 0.f, ls1 = 0.f;
;     ...
;             union PFU { u32x4 u; bf16x8 b; };
;             PFU p0, p1, p2, p3;
;             AT_EXP(s0, 0, p0);
; #pragma unroll
;             for (int kk = 0; kk < 2; ++kk)
; #pragma unroll
;                 for (int db = 0; db < NDB; ++db) vc[kk * NDB + db] = *(const ALAS bf16x8*)(sb + vx[kk + 2] + db * 4096);
;             __builtin_amdgcn_sched_barrier(0);
; #pragma unroll
;             for (int db = 0; db < NDB; ++db) o[db] = __builtin_amdgcn_mfma_f32_32x32x16_bf16(va[db], p0.b, o[db], 0, 0, 0);
;             AT_EXP(s0, 8, p1);
;             __builtin_amdgcn_sched_barrier(0);
; #pragma unroll
;             for (int db = 0; db < NDB; ++db) o[db] = __builtin_amdgcn_mfma_f32_32x32x16_bf16(va[NDB + db], p1.b, o[db], 0, 0, 0);
;             AT_EXP(s1, 0, p2);
;             __builtin_amdgcn_sched_barrier(0);
; #pragma unroll
;             for (int db = 0; db < NDB; ++db) o[db] = __builtin_amdgcn_mfma_f32_32x32x16_bf16(vc[db], p2.b, o[db], 0, 0, 0);
;             AT_EXP(s1, 8, p3);
;             __builtin_amdgcn_sched_barrier(0);
; #pragma unroll
;             for (int db = 0; db < NDB; ++db) o[db] = __builtin_amdgcn_mfma_f32_32x32x16_bf16(vc[NDB + db], p3.b, o[db], 0, 0, 0);
;             __builtin_amdgcn_sched_barrier(0);
;     ...
;             l_run += ls0 + ls1;
.LSPp_pv:
	s_cmp_eq_u32 s86, 0
	s_cbranch_scc1 .LSPp_pure
	s_waitcnt lgkmcnt(4)
	v_mfma_f32_32x32x16_bf16 v[50:65], v[130:133], v[238:241], v[50:65]
	v_exp_f32_e32 v98, v98
	v_exp_f32_e32 v99, v99
	v_mfma_f32_32x32x16_bf16 v[34:49], v[134:137], v[238:241], v[34:49]
	v_exp_f32_e32 v100, v100
	v_exp_f32_e32 v101, v101
	v_mfma_f32_32x32x16_bf16 v[18:33], v[138:141], v[238:241], v[18:33]
	v_exp_f32_e32 v102, v102
	v_exp_f32_e32 v103, v103
	v_add_f32_e32 v228, v98, v100
	v_add_f32_e32 v229, v99, v101
	v_mfma_f32_32x32x16_bf16 v[2:17], v[142:145], v[238:241], v[2:17]
	v_exp_f32_e32 v104, v104
	v_exp_f32_e32 v105, v105
	v_add_f32_e32 v228, v228, v102
	v_add_f32_e32 v229, v229, v103
	v_add3_u32 v236, s99, v183, v187
	ds_read_b128 v[130:133], v236 offset:16384
	ds_read_b128 v[134:137], v236 offset:20480
	ds_read_b128 v[138:141], v236 offset:24576
	ds_read_b128 v[142:145], v236 offset:28672
	s_waitcnt lgkmcnt(4)
	v_mfma_f32_32x32x16_bf16 v[50:65], v[146:149], v[242:245], v[50:65]
	v_exp_f32_e32 v106, v106
	v_exp_f32_e32 v107, v107
	v_add_f32_e32 v228, v228, v104
	v_add_f32_e32 v229, v229, v105
	v_cvt_pk_bf16_f32 v238, v98, v99
	v_lshl_add_u64 v[174:175], v[174:175], 0, s[60:61]
	s_add_i32 s87, s85, 0xffff8000
	s_and_b32 s87, s87, 0x18000
	v_mfma_f32_32x32x16_bf16 v[34:49], v[150:153], v[242:245], v[34:49]
	v_exp_f32_e32 v108, v108
	v_exp_f32_e32 v109, v109
	v_add_f32_e32 v228, v228, v106
	v_add_f32_e32 v229, v229, v107
	v_cvt_pk_bf16_f32 v239, v100, v101
	v_lshl_add_u64 v[172:173], v[172:173], 0, s[48:49]
	s_add_i32 s98, s85, 0x10000
	s_and_b32 s98, s98, 0x18000
	v_mfma_f32_32x32x16_bf16 v[18:33], v[154:157], v[242:245], v[18:33]
	v_exp_f32_e32 v110, v110
	v_exp_f32_e32 v111, v111
	v_add_f32_e32 v228, v228, v108
	v_add_f32_e32 v229, v229, v109
	v_cvt_pk_bf16_f32 v240, v102, v103
	v_lshl_add_u64 v[208:209], v[174:175], 0, s[40:41]
	s_add_i32 s98, s98, s20
	s_add_i32 s101, s85, 0x8000
	v_mfma_f32_32x32x16_bf16 v[2:17], v[158:161], v[242:245], v[2:17]
	v_exp_f32_e32 v112, v112
	v_exp_f32_e32 v113, v113
	v_add_f32_e32 v228, v228, v110
	v_add_f32_e32 v229, v229, v111
	v_cvt_pk_bf16_f32 v241, v104, v105
	v_lshl_add_u64 v[210:211], v[172:173], 0, s[40:41]
	s_and_b32 s101, s101, 0x18000
	s_add_i32 s101, s101, s20
	v_add3_u32 v237, s99, v190, v187
	ds_read_b128 v[146:149], v237 offset:16384
	ds_read_b128 v[150:153], v237 offset:20480
	ds_read_b128 v[154:157], v237 offset:24576
	ds_read_b128 v[158:161], v237 offset:28672
	s_waitcnt lgkmcnt(4)
	v_mfma_f32_32x32x16_bf16 v[50:65], v[130:133], v[246:249], v[50:65]
	v_exp_f32_e32 v82, v82
	v_exp_f32_e32 v83, v83
	v_add_f32_e32 v228, v228, v112
	v_add_f32_e32 v229, v229, v113
	v_cvt_pk_bf16_f32 v242, v106, v107
	v_add3_u32 v212, s87, v178, v162
	s_add_i32 s99, s81, s83
	s_add_i32 s99, s99, 64
	s_sub_i32 m0, s82, 64
	v_mfma_f32_32x32x16_bf16 v[34:49], v[134:137], v[246:249], v[34:49]
	v_exp_f32_e32 v84, v84
	v_exp_f32_e32 v85, v85
	v_add_f32_e32 v228, v228, v82
	v_add_f32_e32 v229, v229, v83
	v_cvt_pk_bf16_f32 v243, v108, v109
	v_add3_u32 v213, s87, v180, v162
	s_max_i32 s99, s99, m0
	s_add_i32 m0, s83, 64
	s_cmp_gt_i32 m0, s78
	v_mfma_f32_32x32x16_bf16 v[18:33], v[138:141], v[246:249], v[18:33]
	v_exp_f32_e32 v86, v86
	v_exp_f32_e32 v87, v87
	v_add_f32_e32 v228, v228, v84
	v_add_f32_e32 v229, v229, v85
	v_cvt_pk_bf16_f32 v244, v110, v111
	v_add3_u32 v214, s87, v182, v162
	s_cselect_b32 m0, s80, s79
	s_cmpk_lt_i32 s99, 0x80
	s_cselect_b32 s65, 1, 0
	v_mfma_f32_32x32x16_bf16 v[2:17], v[142:145], v[246:249], v[2:17]
	v_exp_f32_e32 v88, v88
	v_exp_f32_e32 v89, v89
	v_add_f32_e32 v228, v228, v86
	v_add_f32_e32 v229, v229, v87
	v_cvt_pk_bf16_f32 v245, v112, v113
	v_add3_u32 v215, s87, v184, v162
	s_cselect_b32 m0, 0, m0
	s_add_i32 s99, s85, 0xffff0000
	s_and_b32 s99, s99, 0x18000
	s_waitcnt lgkmcnt(0)
	v_mfma_f32_32x32x16_bf16 v[50:65], v[146:149], v[250:253], v[50:65]
	v_exp_f32_e32 v90, v90
	v_exp_f32_e32 v91, v91
	v_add_f32_e32 v228, v228, v88
	v_add_f32_e32 v229, v229, v89
	v_cvt_pk_bf16_f32 v246, v82, v83
	s_add_i32 s86, s86, 1
	s_add_i32 s85, s85, 0x8000
	s_addk_i32 s84, 0x100
	v_mfma_f32_32x32x16_bf16 v[34:49], v[150:153], v[250:253], v[34:49]
	v_exp_f32_e32 v92, v92
	v_exp_f32_e32 v93, v93
	v_add_f32_e32 v228, v228, v90
	v_add_f32_e32 v229, v229, v91
	v_cvt_pk_bf16_f32 v247, v84, v85
	s_add_i32 s83, s83, 64
	s_sub_i32 s82, s82, 64
	v_mfma_f32_32x32x16_bf16 v[18:33], v[154:157], v[250:253], v[18:33]
	v_exp_f32_e32 v94, v94
	v_exp_f32_e32 v95, v95
	v_add_f32_e32 v228, v228, v92
	v_add_f32_e32 v229, v229, v93
	v_cvt_pk_bf16_f32 v248, v86, v87
	v_mfma_f32_32x32x16_bf16 v[2:17], v[158:161], v[250:253], v[2:17]
	v_exp_f32_e32 v96, v96
	v_exp_f32_e32 v97, v97
	v_add_f32_e32 v228, v228, v94
	v_add_f32_e32 v229, v229, v95
	v_cvt_pk_bf16_f32 v249, v88, v89
	v_add_f32_e32 v228, v228, v96
	v_add_f32_e32 v229, v229, v97
	v_cvt_pk_bf16_f32 v250, v90, v91
	v_cvt_pk_bf16_f32 v251, v92, v93
	v_cvt_pk_bf16_f32 v252, v94, v95
	v_cvt_pk_bf16_f32 v253, v96, v97
	ds_read_b128 v[130:133], v212
	ds_read_b128 v[134:137], v212 offset:4096
	ds_read_b128 v[138:141], v213
	ds_read_b128 v[142:145], v213 offset:4096
	ds_read_b128 v[146:149], v214
	ds_read_b128 v[150:153], v214 offset:4096
	ds_read_b128 v[158:161], v215
	ds_read_b128 v[204:207], v215 offset:4096
	v_add_f32_e32 v228, v228, v229
	v_cmp_nge_f32_e32 vcc, 0x53800000, v228
	s_cbranch_vccnz .LSPp_redo
	v_add_f32_e32 v0, v0, v228
	s_cmpk_eq_u32 s84, 0x8000
	s_cbranch_scc0 .LSPp_top
	s_branch .LSPp_exit
; #define ALAS __attribute__((address_space(3)))
; template <int N> __device__ __forceinline__ void wait_bar() { asm volatile("s_waitcnt vmcnt(%0) lgkmcnt(0)\n\ts_barrier" :: "n"(N) : "memory"); }
; template <bool WIN> ...
;     ...
;     for (int tr = 0; tr < NT; ++tr) {
;         if (tr + 2 < NT) wait_bar<2 * NPW>(); else if (tr + 1 < NT) wait_bar<NPW>(); else wait_bar<0>();
;         if (tr + 3 < NT) AT_DMA(tr + 3);
;         const int k0 = (t_lo + tr) * 64;
;         const bool skip = WIN && (k0 > qw + 31 + 128 || k0 + 63 < qw - 128);
;         if (!skip) {
;             const bool near = WIN || ((k0 - (qw + 31)) < 128 && (qw - (k0 + 63)) < 128);
;             const float cinit = near ? 0.f : (k0 > qw ? cfar_hi : cfar_lo);
;     ...
;             float ls0 = 0.f, ls1 = 0.f;
;     ...
;             union PFU { u32x4 u; bf16x8 b; };
;             PFU p0, p1, p2, p3;
;             AT_EXP(s0, 0, p0);
; #pragma unroll
;             for (int kk = 0; kk < 2; ++kk)
; #pragma unroll
;                 for (int db = 0; db < NDB; ++db) vc[kk * NDB + db] = *(const ALAS bf16x8*)(sb + vx[kk + 2] + db * 4096);
;             __builtin_amdgcn_sched_barrier(0);
; #pragma unroll
;             for (int db = 0; db < NDB; ++db) o[db] = __builtin_amdgcn_mfma_f32_32x32x16_bf16(va[db], p0.b, o[db], 0, 0, 0);
;             AT_EXP(s0, 8, p1);
;             __builtin_amdgcn_sched_barrier(0);
; #pragma unroll
;             for (int db = 0; db < NDB; ++db) o[db] = __builtin_amdgcn_mfma_f32_32x32x16_bf16(va[NDB + db], p1.b, o[db], 0, 0, 0);
;             AT_EXP(s1, 0, p2);
;             __builtin_amdgcn_sched_barrier(0);
; #pragma unroll
;             for (int db = 0; db < NDB; ++db) o[db] = __builtin_amdgcn_mfma_f32_32x32x16_bf16(vc[db], p2.b, o[db], 0, 0, 0);
;             AT_EXP(s1, 8, p3);
;             __builtin_amdgcn_sched_barrier(0);
; #pragma unroll
;             for (int db = 0; db < NDB; ++db) o[db] = __builtin_amdgcn_mfma_f32_32x32x16_bf16(vc[NDB + db], p3.b, o[db], 0, 0, 0);
;             __builtin_amdgcn_sched_barrier(0);
;     ...
;             l_run += ls0 + ls1;
.LSPp_pure:
	v_lshl_add_u64 v[174:175], v[174:175], 0, s[60:61]
	v_lshl_add_u64 v[172:173], v[172:173], 0, s[48:49]
	s_add_i32 s98, s85, 0x10000
	s_and_b32 s98, s98, 0x18000
	s_add_i32 s98, s98, s20
	s_add_i32 s101, s85, 0x8000
	s_and_b32 s101, s101, 0x18000
	s_add_i32 s101, s101, s20
	v_lshl_add_u64 v[208:209], v[174:175], 0, s[40:41]
	v_lshl_add_u64 v[210:211], v[172:173], 0, s[40:41]
	s_add_i32 s87, s85, 0xffff8000
	s_and_b32 s87, s87, 0x18000
	v_add3_u32 v212, s87, v178, v162
	v_add3_u32 v213, s87, v180, v162
	v_add3_u32 v214, s87, v182, v162
	v_add3_u32 v215, s87, v184, v162
	s_add_i32 s99, s81, s83
	s_add_i32 s99, s99, 64
	s_sub_i32 m0, s82, 64
	s_max_i32 s99, s99, m0
	s_add_i32 m0, s83, 64
	s_cmp_gt_i32 m0, s78
	s_cselect_b32 m0, s80, s79
	s_cmpk_lt_i32 s99, 0x80
	s_cselect_b32 s65, 1, 0
	s_cselect_b32 m0, 0, m0
	s_add_i32 s99, s85, 0xffff0000
	s_and_b32 s99, s99, 0x18000
	s_add_i32 s86, s86, 1
	s_add_i32 s85, s85, 0x8000
	s_addk_i32 s84, 0x100
	s_add_i32 s83, s83, 64
	s_sub_i32 s82, s82, 64
	v_exp_f32_e32 v98, v98
	v_exp_f32_e32 v99, v99
	v_exp_f32_e32 v100, v100
	v_exp_f32_e32 v101, v101
	v_exp_f32_e32 v102, v102
	v_exp_f32_e32 v103, v103
	v_exp_f32_e32 v104, v104
	v_exp_f32_e32 v105, v105
	v_cvt_pk_bf16_f32 v238, v98, v99
	v_cvt_pk_bf16_f32 v239, v100, v101
	v_cvt_pk_bf16_f32 v240, v102, v103
	v_cvt_pk_bf16_f32 v241, v104, v105
	v_mov_b32_e32 v228, v98
	v_mov_b32_e32 v229, v102
	v_add_f32_e32 v228, v228, v99
	v_add_f32_e32 v229, v229, v103
	v_add_f32_e32 v228, v228, v100
	v_add_f32_e32 v229, v229, v104
	v_add_f32_e32 v228, v228, v101
	v_add_f32_e32 v229, v229, v105
	v_exp_f32_e32 v106, v106
	v_exp_f32_e32 v107, v107
	v_exp_f32_e32 v108, v108
	v_exp_f32_e32 v109, v109
	v_exp_f32_e32 v110, v110
	v_exp_f32_e32 v111, v111
	v_exp_f32_e32 v112, v112
	v_exp_f32_e32 v113, v113
	v_cvt_pk_bf16_f32 v242, v106, v107
	v_cvt_pk_bf16_f32 v243, v108, v109
	v_cvt_pk_bf16_f32 v244, v110, v111
	v_cvt_pk_bf16_f32 v245, v112, v113
	v_add_f32_e32 v228, v228, v106
	v_add_f32_e32 v229, v229, v110
	v_add_f32_e32 v228, v228, v107
	v_add_f32_e32 v229, v229, v111
	v_add_f32_e32 v228, v228, v108
	v_add_f32_e32 v229, v229, v112
	v_add_f32_e32 v228, v228, v109
	v_add_f32_e32 v229, v229, v113
	v_exp_f32_e32 v82, v82
	v_exp_f32_e32 v83, v83
	v_exp_f32_e32 v84, v84
	v_exp_f32_e32 v85, v85
	v_exp_f32_e32 v86, v86
	v_exp_f32_e32 v87, v87
	v_exp_f32_e32 v88, v88
	v_exp_f32_e32 v89, v89
	v_cvt_pk_bf16_f32 v246, v82, v83
	v_cvt_pk_bf16_f32 v247, v84, v85
	v_cvt_pk_bf16_f32 v248, v86, v87
	v_cvt_pk_bf16_f32 v249, v88, v89
	v_add_f32_e32 v228, v228, v82
	v_add_f32_e32 v229, v229, v86
	v_add_f32_e32 v228, v228, v83
	v_add_f32_e32 v229, v229, v87
	v_add_f32_e32 v228, v228, v84
	v_add_f32_e32 v229, v229, v88
	v_add_f32_e32 v228, v228, v85
	v_add_f32_e32 v229, v229, v89
	v_exp_f32_e32 v90, v90
	v_exp_f32_e32 v91, v91
	v_exp_f32_e32 v92, v92
	v_exp_f32_e32 v93, v93
	v_exp_f32_e32 v94, v94
	v_exp_f32_e32 v95, v95
	v_exp_f32_e32 v96, v96
	v_exp_f32_e32 v97, v97
	v_cvt_pk_bf16_f32 v250, v90, v91
	v_cvt_pk_bf16_f32 v251, v92, v93
	v_cvt_pk_bf16_f32 v252, v94, v95
	v_cvt_pk_bf16_f32 v253, v96, v97
	v_add_f32_e32 v228, v228, v90
	v_add_f32_e32 v229, v229, v94
	v_add_f32_e32 v228, v228, v91
	v_add_f32_e32 v229, v229, v95
	v_add_f32_e32 v228, v228, v92
	v_add_f32_e32 v229, v229, v96
	v_add_f32_e32 v228, v228, v93
	v_add_f32_e32 v229, v229, v97
	ds_read_b128 v[130:133], v212
	ds_read_b128 v[134:137], v212 offset:4096
	ds_read_b128 v[138:141], v213
	ds_read_b128 v[142:145], v213 offset:4096
	ds_read_b128 v[146:149], v214
	ds_read_b128 v[150:153], v214 offset:4096
	ds_read_b128 v[158:161], v215
	ds_read_b128 v[204:207], v215 offset:4096
	v_add_f32_e32 v228, v228, v229
	v_cmp_nge_f32_e32 vcc, 0x53800000, v228
	s_cbranch_vccnz .LSPp_redo
	v_add_f32_e32 v0, v0, v228
	s_cmpk_eq_u32 s84, 0x8000
	s_cbranch_scc0 .LSPp_top
	s_branch .LSPp_exit
; #define ALAS __attribute__((address_space(3)))
; template <bool WIN> ...
;     ...
;             {
;                 bf16x8 ka[8];
; #pragma unroll
;                 for (int ds = 0; ds < 4; ++ds) { ka[2 * ds] = *(const ALAS bf16x8*)(sb + kx[ds]); ka[2 * ds + 1] = *(const ALAS bf16x8*)(sb + kx[ds] + 4096); }
;                 __builtin_amdgcn_sched_barrier(0);
;                 s0 = __builtin_amdgcn_mfma_f32_32x32x16_bf16(ka[0], qf(0), cvec, 0, 0, 0);
;                 s1 = __builtin_amdgcn_mfma_f32_32x32x16_bf16(ka[1], qf(0), cvec, 0, 0, 0);
; #pragma unroll
;                 for (int ds = 1; ds < 4; ++ds) {
;                     s0 = __builtin_amdgcn_mfma_f32_32x32x16_bf16(ka[2 * ds], qf(ds), s0, 0, 0, 0);
;                     s1 = __builtin_amdgcn_mfma_f32_32x32x16_bf16(ka[2 * ds + 1], qf(ds), s1, 0, 0, 0);
;                 }
;             }
;             bf16x8 va[2 * NDB], vc[2 * NDB];
; #pragma unroll
;             for (int kk = 0; kk < 2; ++kk)
; #pragma unroll
;                 for (int db = 0; db < NDB; ++db) va[kk * NDB + db] = *(const ALAS bf16x8*)(sb + vx[kk] + db * 4096);
;             __builtin_amdgcn_sched_barrier(0);
;             if (near) {
;                 const ALAS float* lb = lut + (k0 + 8 * hi - qabs + LUTC);
; #pragma unroll
;                 for (int r = 0; r < 16; ++r) { s0[r] += lb[16 * (r >> 3) + (r & 7)]; s1[r] += lb[32 + 16 * (r >> 3) + (r & 7)];
;                     if ((r & 7) == 7) __builtin_amdgcn_sched_barrier(0); }
;             }
.LSPp_redo:
	s_add_i32 s87, s85, 0xfffe8000
	s_and_b32 s87, s87, 0x18000
	v_add3_u32 v203, s87, v178, v162
	ds_read_b128 v[130:133], v203
	ds_read_b128 v[134:137], v203 offset:4096
	v_add3_u32 v203, s87, v180, v162
	ds_read_b128 v[138:141], v203
	ds_read_b128 v[142:145], v203 offset:4096
	v_add3_u32 v203, s87, v182, v162
	ds_read_b128 v[146:149], v203
	ds_read_b128 v[150:153], v203 offset:4096
	v_add3_u32 v203, s87, v184, v162
	ds_read_b128 v[158:161], v203
	ds_read_b128 v[204:207], v203 offset:4096
	s_waitcnt lgkmcnt(0)
	v_mfma_f32_32x32x16_bf16 v[98:113], v[130:133], v[126:129], v[66:81]
	v_mfma_f32_32x32x16_bf16 v[82:97], v[134:137], v[126:129], v[66:81]
	v_mfma_f32_32x32x16_bf16 v[98:113], v[138:141], v[122:125], v[98:113]
	v_mfma_f32_32x32x16_bf16 v[82:97], v[142:145], v[122:125], v[82:97]
	v_mfma_f32_32x32x16_bf16 v[98:113], v[146:149], v[118:121], v[98:113]
	v_mfma_f32_32x32x16_bf16 v[82:97], v[150:153], v[118:121], v[82:97]
	v_mfma_f32_32x32x16_bf16 v[98:113], v[158:161], v[114:117], v[98:113]
	v_mfma_f32_32x32x16_bf16 v[82:97], v[204:207], v[114:117], v[82:97]
	s_nop 7
	s_nop 7
	s_cmp_eq_u32 s64, 0
	s_cbranch_scc1 .LSPp_redomax
	s_addk_i32 s84, 0xff00
	v_add_u32_e32 v203, s84, v171
	v_add_u32_e32 v204, 0x23b80, v203
	v_add_u32_e32 v206, 0x23c00, v203
	v_add_u32_e32 v210, 0x23c08, v203
	v_add_u32_e32 v208, 0x23b88, v203
	v_add_u32_e32 v218, 0x23c10, v203
	v_add_u32_e32 v212, 0x23b90, v203
	v_add_u32_e32 v216, 0x23c18, v203
	v_add_u32_e32 v214, 0x23b98, v203
	ds_read2_b32 v[204:205], v204 offset1:1
	ds_read2_b32 v[206:207], v206 offset1:1
	ds_read2_b32 v[208:209], v208 offset1:1
	ds_read2_b32 v[210:211], v210 offset1:1
	ds_read2_b32 v[212:213], v212 offset1:1
	ds_read2_b32 v[214:215], v214 offset1:1
	ds_read2_b32 v[216:217], v216 offset1:1
	ds_read2_b32 v[218:219], v218 offset1:1
	v_add_u32_e32 v220, 0x23bc0, v203
	v_add_u32_e32 v222, 0x23c40, v203
	v_add_u32_e32 v226, 0x23c48, v203
	v_add_u32_e32 v224, 0x23bc8, v203
	v_add_u32_e32 v228, 0x23bd0, v203
	v_add_u32_e32 v234, 0x23c58, v203
	ds_read2_b32 v[220:221], v220 offset1:1
	ds_read2_b32 v[222:223], v222 offset1:1
	ds_read2_b32 v[224:225], v224 offset1:1
	ds_read2_b32 v[226:227], v226 offset1:1
	v_add_u32_e32 v231, 0x23c50, v203
	v_add_u32_e32 v203, 0x23bd8, v203
	ds_read2_b32 v[228:229], v228 offset1:1
	ds_read2_b32 v[232:233], v203 offset1:1
	ds_read2_b32 v[234:235], v234 offset1:1
	ds_read2_b32 v[236:237], v231 offset1:1
	s_waitcnt lgkmcnt(10)
	v_pk_add_f32 v[104:105], v[104:105], v[214:215]
	v_pk_add_f32 v[102:103], v[102:103], v[212:213]
	v_pk_add_f32 v[100:101], v[100:101], v[208:209]
	s_waitcnt lgkmcnt(2)
	v_pk_add_f32 v[112:113], v[112:113], v[232:233]
	v_pk_add_f32 v[110:111], v[110:111], v[228:229]
	v_pk_add_f32 v[108:109], v[108:109], v[224:225]
	v_pk_add_f32 v[106:107], v[106:107], v[220:221]
	v_pk_add_f32 v[98:99], v[98:99], v[204:205]
	v_pk_add_f32 v[88:89], v[88:89], v[216:217]
	v_pk_add_f32 v[86:87], v[86:87], v[218:219]
	v_pk_add_f32 v[84:85], v[84:85], v[210:211]
	s_waitcnt lgkmcnt(1)
	v_pk_add_f32 v[96:97], v[96:97], v[234:235]
	s_waitcnt lgkmcnt(0)
	v_pk_add_f32 v[94:95], v[94:95], v[236:237]
	v_pk_add_f32 v[92:93], v[92:93], v[226:227]
	v_pk_add_f32 v[90:91], v[90:91], v[222:223]
	v_pk_add_f32 v[82:83], v[82:83], v[206:207]
	s_addk_i32 s84, 0x100

; #define ALAS __attribute__((address_space(3)))
; template <bool WIN> ...
;     ...
;             float ls0 = 0.f, ls1 = 0.f;
;     ...
;             union PFU { u32x4 u; bf16x8 b; };
;             PFU p0, p1, p2, p3;
;             AT_EXP(s0, 0, p0);
; #pragma unroll
;             for (int kk = 0; kk < 2; ++kk)
; #pragma unroll
;                 for (int db = 0; db < NDB; ++db) vc[kk * NDB + db] = *(const ALAS bf16x8*)(sb + vx[kk + 2] + db * 4096);
;             __builtin_amdgcn_sched_barrier(0);
; #pragma unroll
;             for (int db = 0; db < NDB; ++db) o[db] = __builtin_amdgcn_mfma_f32_32x32x16_bf16(va[db], p0.b, o[db], 0, 0, 0);
;             AT_EXP(s0, 8, p1);
;             __builtin_amdgcn_sched_barrier(0);
; #pragma unroll
;             for (int db = 0; db < NDB; ++db) o[db] = __builtin_amdgcn_mfma_f32_32x32x16_bf16(va[NDB + db], p1.b, o[db], 0, 0, 0);
;             AT_EXP(s1, 0, p2);
;             __builtin_amdgcn_sched_barrier(0);
; #pragma unroll
;             for (int db = 0; db < NDB; ++db) o[db] = __builtin_amdgcn_mfma_f32_32x32x16_bf16(vc[db], p2.b, o[db], 0, 0, 0);
;             AT_EXP(s1, 8, p3);
;             __builtin_amdgcn_sched_barrier(0);
; #pragma unroll
;             for (int db = 0; db < NDB; ++db) o[db] = __builtin_amdgcn_mfma_f32_32x32x16_bf16(vc[NDB + db], p3.b, o[db], 0, 0, 0);
;             __builtin_amdgcn_sched_barrier(0);
;     ...
;             l_run += ls0 + ls1;
.LSPp_pure2:
	s_add_i32 s87, s85, 0xffff0000
	s_and_b32 s87, s87, 0x18000
	v_lshl_add_u64 v[208:209], v[174:175], 0, s[40:41]
	v_lshl_add_u64 v[210:211], v[172:173], 0, s[40:41]
	v_add3_u32 v212, s87, v178, v162
	v_add3_u32 v213, s87, v180, v162
	v_add3_u32 v214, s87, v182, v162
	v_add3_u32 v215, s87, v184, v162
	v_exp_f32_e32 v98, v98
	v_exp_f32_e32 v99, v99
	v_exp_f32_e32 v100, v100
	v_exp_f32_e32 v101, v101
	v_exp_f32_e32 v102, v102
	v_exp_f32_e32 v103, v103
	v_exp_f32_e32 v104, v104
	v_exp_f32_e32 v105, v105
	v_cvt_pk_bf16_f32 v238, v98, v99
	v_cvt_pk_bf16_f32 v239, v100, v101
	v_cvt_pk_bf16_f32 v240, v102, v103
	v_cvt_pk_bf16_f32 v241, v104, v105
	v_mov_b32_e32 v228, v98
	v_mov_b32_e32 v229, v102
	v_add_f32_e32 v228, v228, v99
	v_add_f32_e32 v229, v229, v103
	v_add_f32_e32 v228, v228, v100
	v_add_f32_e32 v229, v229, v104
	v_add_f32_e32 v228, v228, v101
	v_add_f32_e32 v229, v229, v105
	v_exp_f32_e32 v106, v106
	v_exp_f32_e32 v107, v107
	v_exp_f32_e32 v108, v108
	v_exp_f32_e32 v109, v109
	v_exp_f32_e32 v110, v110
	v_exp_f32_e32 v111, v111
	v_exp_f32_e32 v112, v112
	v_exp_f32_e32 v113, v113
	v_cvt_pk_bf16_f32 v242, v106, v107
	v_cvt_pk_bf16_f32 v243, v108, v109
	v_cvt_pk_bf16_f32 v244, v110, v111
	v_cvt_pk_bf16_f32 v245, v112, v113
	v_add_f32_e32 v228, v228, v106
	v_add_f32_e32 v229, v229, v110
	v_add_f32_e32 v228, v228, v107
	v_add_f32_e32 v229, v229, v111
	v_add_f32_e32 v228, v228, v108
	v_add_f32_e32 v229, v229, v112
	v_add_f32_e32 v228, v228, v109
	v_add_f32_e32 v229, v229, v113
	v_exp_f32_e32 v82, v82
	v_exp_f32_e32 v83, v83
	v_exp_f32_e32 v84, v84
	v_exp_f32_e32 v85, v85
	v_exp_f32_e32 v86, v86
	v_exp_f32_e32 v87, v87
	v_exp_f32_e32 v88, v88
	v_exp_f32_e32 v89, v89
	v_cvt_pk_bf16_f32 v246, v82, v83
	v_cvt_pk_bf16_f32 v247, v84, v85
	v_cvt_pk_bf16_f32 v248, v86, v87
	v_cvt_pk_bf16_f32 v249, v88, v89
	v_add_f32_e32 v228, v228, v82
	v_add_f32_e32 v229, v229, v86
	v_add_f32_e32 v228, v228, v83
	v_add_f32_e32 v229, v229, v87
	v_add_f32_e32 v228, v228, v84
	v_add_f32_e32 v229, v229, v88
	v_add_f32_e32 v228, v228, v85
	v_add_f32_e32 v229, v229, v89
	v_exp_f32_e32 v90, v90
	v_exp_f32_e32 v91, v91
	v_exp_f32_e32 v92, v92
	v_exp_f32_e32 v93, v93
	v_exp_f32_e32 v94, v94
	v_exp_f32_e32 v95, v95
	v_exp_f32_e32 v96, v96
	v_exp_f32_e32 v97, v97
	v_cvt_pk_bf16_f32 v250, v90, v91
	v_cvt_pk_bf16_f32 v251, v92, v93
	v_cvt_pk_bf16_f32 v252, v94, v95
	v_cvt_pk_bf16_f32 v253, v96, v97
	v_add_f32_e32 v228, v228, v90
	v_add_f32_e32 v229, v229, v94
	v_add_f32_e32 v228, v228, v91
	v_add_f32_e32 v229, v229, v95
	v_add_f32_e32 v228, v228, v92
	v_add_f32_e32 v229, v229, v96
	v_add_f32_e32 v228, v228, v93
	v_add_f32_e32 v229, v229, v97
	ds_read_b128 v[130:133], v212
	ds_read_b128 v[134:137], v212 offset:4096
	ds_read_b128 v[138:141], v213
	ds_read_b128 v[142:145], v213 offset:4096
	ds_read_b128 v[146:149], v214
	ds_read_b128 v[150:153], v214 offset:4096
	ds_read_b128 v[158:161], v215
	ds_read_b128 v[204:207], v215 offset:4096
	v_add_f32_e32 v228, v228, v229
	v_add_f32_e32 v0, v0, v228
	s_cmpk_eq_u32 s84, 0x8000
	s_cbranch_scc0 .LSPp_top
	s_branch .LSPp_exit

; #define ALAS __attribute__((address_space(3)))
; template <int N> __device__ __forceinline__ void wait_bar() { asm volatile("s_waitcnt vmcnt(%0) lgkmcnt(0)\n\ts_barrier" :: "n"(N) : "memory"); }
; template <bool WIN> ...
;     ...
;     for (int tr = 0; tr < NT; ++tr) {
;         if (tr + 2 < NT) wait_bar<2 * NPW>(); else if (tr + 1 < NT) wait_bar<NPW>(); else wait_bar<0>();
;         if (tr + 3 < NT) AT_DMA(tr + 3);
;         const int k0 = (t_lo + tr) * 64;
;         const bool skip = WIN && (k0 > qw + 31 + 128 || k0 + 63 < qw - 128);
;         if (!skip) {
;             const bool near = WIN || ((k0 - (qw + 31)) < 128 && (qw - (k0 + 63)) < 128);
;             const float cinit = near ? 0.f : (k0 > qw ? cfar_hi : cfar_lo);
;     ...
;             float ls0 = 0.f, ls1 = 0.f;
;     ...
;             union PFU { u32x4 u; bf16x8 b; };
;             PFU p0, p1, p2, p3;
;             AT_EXP(s0, 0, p0);
; #pragma unroll
;             for (int kk = 0; kk < 2; ++kk)
; #pragma unroll
;                 for (int db = 0; db < NDB; ++db) vc[kk * NDB + db] = *(const ALAS bf16x8*)(sb + vx[kk + 2] + db * 4096);
;             __builtin_amdgcn_sched_barrier(0);
; #pragma unroll
;             for (int db = 0; db < NDB; ++db) o[db] = __builtin_amdgcn_mfma_f32_32x32x16_bf16(va[db], p0.b, o[db], 0, 0, 0);
;             AT_EXP(s0, 8, p1);
;             __builtin_amdgcn_sched_barrier(0);
; #pragma unroll
;             for (int db = 0; db < NDB; ++db) o[db] = __builtin_amdgcn_mfma_f32_32x32x16_bf16(va[NDB + db], p1.b, o[db], 0, 0, 0);
;             AT_EXP(s1, 0, p2);
;             __builtin_amdgcn_sched_barrier(0);
; #pragma unroll
;             for (int db = 0; db < NDB; ++db) o[db] = __builtin_amdgcn_mfma_f32_32x32x16_bf16(vc[db], p2.b, o[db], 0, 0, 0);
;             AT_EXP(s1, 8, p3);
;             __builtin_amdgcn_sched_barrier(0);
; #pragma unroll
;             for (int db = 0; db < NDB; ++db) o[db] = __builtin_amdgcn_mfma_f32_32x32x16_bf16(vc[NDB + db], p3.b, o[db], 0, 0, 0);
;             __builtin_amdgcn_sched_barrier(0);
;     ...
;             l_run += ls0 + ls1;
.LSPs_pv:
	s_cmp_eq_u32 s79, 0
	s_cbranch_scc1 .LSPs_pure
	s_waitcnt lgkmcnt(4)
	v_mfma_f32_32x32x16_bf16 v[50:65], v[130:133], v[238:241], v[50:65]
	v_exp_f32_e32 v98, v98
	v_exp_f32_e32 v99, v99
	v_mfma_f32_32x32x16_bf16 v[34:49], v[134:137], v[238:241], v[34:49]
	v_exp_f32_e32 v100, v100
	v_exp_f32_e32 v101, v101
	v_mfma_f32_32x32x16_bf16 v[18:33], v[138:141], v[238:241], v[18:33]
	v_exp_f32_e32 v102, v102
	v_exp_f32_e32 v103, v103
	v_add_f32_e32 v228, v98, v100
	v_add_f32_e32 v229, v99, v101
	v_mfma_f32_32x32x16_bf16 v[2:17], v[142:145], v[238:241], v[2:17]
	v_exp_f32_e32 v104, v104
	v_exp_f32_e32 v105, v105
	v_add_f32_e32 v228, v228, v102
	v_add_f32_e32 v229, v229, v103
	v_add3_u32 v236, s99, v183, v187
	ds_read_b128 v[130:133], v236 offset:16384
	ds_read_b128 v[134:137], v236 offset:20480
	ds_read_b128 v[138:141], v236 offset:24576
	ds_read_b128 v[142:145], v236 offset:28672
	s_waitcnt lgkmcnt(4)
	v_mfma_f32_32x32x16_bf16 v[50:65], v[146:149], v[242:245], v[50:65]
	v_exp_f32_e32 v106, v106
	v_exp_f32_e32 v107, v107
	v_add_f32_e32 v228, v228, v104
	v_add_f32_e32 v229, v229, v105
	v_cvt_pk_bf16_f32 v238, v98, v99
	v_lshl_add_u64 v[174:175], v[174:175], 0, s[60:61]
	s_add_i32 s80, s78, 0xffff8000
	s_and_b32 s80, s80, 0x18000
	v_mfma_f32_32x32x16_bf16 v[34:49], v[150:153], v[242:245], v[34:49]
	v_exp_f32_e32 v108, v108
	v_exp_f32_e32 v109, v109
	v_add_f32_e32 v228, v228, v106
	v_add_f32_e32 v229, v229, v107
	v_cvt_pk_bf16_f32 v239, v100, v101
	v_lshl_add_u64 v[172:173], v[172:173], 0, s[48:49]
	s_add_i32 s98, s78, 0x10000
	s_and_b32 s98, s98, 0x18000
	v_mfma_f32_32x32x16_bf16 v[18:33], v[154:157], v[242:245], v[18:33]
	v_exp_f32_e32 v110, v110
	v_exp_f32_e32 v111, v111
	v_add_f32_e32 v228, v228, v108
	v_add_f32_e32 v229, v229, v109
	v_cvt_pk_bf16_f32 v240, v102, v103
	v_lshl_add_u64 v[208:209], v[174:175], 0, s[40:41]
	s_add_i32 s98, s98, s29
	s_add_i32 s101, s78, 0x8000
	v_mfma_f32_32x32x16_bf16 v[2:17], v[158:161], v[242:245], v[2:17]
	v_exp_f32_e32 v112, v112
	v_exp_f32_e32 v113, v113
	v_add_f32_e32 v228, v228, v110
	v_add_f32_e32 v229, v229, v111
	v_cvt_pk_bf16_f32 v241, v104, v105
	v_lshl_add_u64 v[210:211], v[172:173], 0, s[40:41]
	s_and_b32 s101, s101, 0x18000
	s_add_i32 s101, s101, s29
	v_add3_u32 v237, s99, v190, v187
	ds_read_b128 v[146:149], v237 offset:16384
	ds_read_b128 v[150:153], v237 offset:20480
	ds_read_b128 v[154:157], v237 offset:24576
	ds_read_b128 v[158:161], v237 offset:28672
	s_waitcnt lgkmcnt(4)
	v_mfma_f32_32x32x16_bf16 v[50:65], v[130:133], v[246:249], v[50:65]
	v_exp_f32_e32 v82, v82
	v_exp_f32_e32 v83, v83
	v_add_f32_e32 v228, v228, v112
	v_add_f32_e32 v229, v229, v113
	v_cvt_pk_bf16_f32 v242, v106, v107
	v_add3_u32 v212, s80, v178, v162
	s_add_i32 s99, s76, 64
	s_cmp_gt_u32 s99, s28
	s_cselect_b32 m0, s31, s30
	v_mfma_f32_32x32x16_bf16 v[34:49], v[134:137], v[246:249], v[34:49]
	v_exp_f32_e32 v84, v84
	v_exp_f32_e32 v85, v85
	v_add_f32_e32 v228, v228, v82
	v_add_f32_e32 v229, v229, v83
	v_cvt_pk_bf16_f32 v243, v108, v109
	v_add3_u32 v213, s80, v180, v162
	s_cmp_lt_u32 s99, s33
	s_cselect_b32 s65, 1, 0
	s_cmp_gt_i32 s99, s67
	v_mfma_f32_32x32x16_bf16 v[18:33], v[138:141], v[246:249], v[18:33]
	v_exp_f32_e32 v86, v86
	v_exp_f32_e32 v87, v87
	v_add_f32_e32 v228, v228, v84
	v_add_f32_e32 v229, v229, v85
	v_cvt_pk_bf16_f32 v244, v110, v111
	v_add3_u32 v214, s80, v182, v162
	s_cselect_b32 s65, s65, 0
	s_cmp_lg_u32 s65, 0
	s_cselect_b32 m0, 0, m0
	v_mfma_f32_32x32x16_bf16 v[2:17], v[142:145], v[246:249], v[2:17]
	v_exp_f32_e32 v88, v88
	v_exp_f32_e32 v89, v89
	v_add_f32_e32 v228, v228, v86
	v_add_f32_e32 v229, v229, v87
	v_cvt_pk_bf16_f32 v245, v112, v113
	v_add3_u32 v215, s80, v184, v162
	s_add_i32 s99, s78, 0xffff0000
	s_and_b32 s99, s99, 0x18000
	s_add_i32 s79, s79, 1
	s_waitcnt lgkmcnt(0)
	v_mfma_f32_32x32x16_bf16 v[50:65], v[146:149], v[250:253], v[50:65]
	v_exp_f32_e32 v90, v90
	v_exp_f32_e32 v91, v91
	v_add_f32_e32 v228, v228, v88
	v_add_f32_e32 v229, v229, v89
	v_cvt_pk_bf16_f32 v246, v82, v83
	s_add_i32 s78, s78, 0x8000
	s_addk_i32 s77, 0x100
	s_add_i32 s76, s76, 64
	v_mfma_f32_32x32x16_bf16 v[34:49], v[150:153], v[250:253], v[34:49]
	v_exp_f32_e32 v92, v92
	v_exp_f32_e32 v93, v93
	v_add_f32_e32 v228, v228, v90
	v_add_f32_e32 v229, v229, v91
	v_cvt_pk_bf16_f32 v247, v84, v85
	v_mfma_f32_32x32x16_bf16 v[18:33], v[154:157], v[250:253], v[18:33]
	v_exp_f32_e32 v94, v94
	v_exp_f32_e32 v95, v95
	v_add_f32_e32 v228, v228, v92
	v_add_f32_e32 v229, v229, v93
	v_cvt_pk_bf16_f32 v248, v86, v87
	v_mfma_f32_32x32x16_bf16 v[2:17], v[158:161], v[250:253], v[2:17]
	v_exp_f32_e32 v96, v96
	v_exp_f32_e32 v97, v97
	v_add_f32_e32 v228, v228, v94
	v_add_f32_e32 v229, v229, v95
	v_cvt_pk_bf16_f32 v249, v88, v89
	v_add_f32_e32 v228, v228, v96
	v_add_f32_e32 v229, v229, v97
	v_cvt_pk_bf16_f32 v250, v90, v91
	v_cvt_pk_bf16_f32 v251, v92, v93
	v_cvt_pk_bf16_f32 v252, v94, v95
	v_cvt_pk_bf16_f32 v253, v96, v97
	ds_read_b128 v[130:133], v212
	ds_read_b128 v[134:137], v212 offset:4096
	ds_read_b128 v[138:141], v213
	ds_read_b128 v[142:145], v213 offset:4096
	ds_read_b128 v[146:149], v214
	ds_read_b128 v[150:153], v214 offset:4096
	ds_read_b128 v[158:161], v215
	ds_read_b128 v[204:207], v215 offset:4096
	v_add_f32_e32 v228, v228, v229
	v_cmp_nge_f32_e32 vcc, 0x53800000, v228
	s_cbranch_vccnz .LSPs_redo
	v_add_f32_e32 v0, v0, v228
	s_cmpk_eq_i32 s77, 0x2000
	s_cbranch_scc0 .LSPs_top
	s_branch .LSPs_exit
; #define ALAS __attribute__((address_space(3)))
; template <int N> __device__ __forceinline__ void wait_bar() { asm volatile("s_waitcnt vmcnt(%0) lgkmcnt(0)\n\ts_barrier" :: "n"(N) : "memory"); }
; template <bool WIN> ...
;     ...
;     for (int tr = 0; tr < NT; ++tr) {
;         if (tr + 2 < NT) wait_bar<2 * NPW>(); else if (tr + 1 < NT) wait_bar<NPW>(); else wait_bar<0>();
;         if (tr + 3 < NT) AT_DMA(tr + 3);
;         const int k0 = (t_lo + tr) * 64;
;         const bool skip = WIN && (k0 > qw + 31 + 128 || k0 + 63 < qw - 128);
;         if (!skip) {
;             const bool near = WIN || ((k0 - (qw + 31)) < 128 && (qw - (k0 + 63)) < 128);
;             const float cinit = near ? 0.f : (k0 > qw ? cfar_hi : cfar_lo);
;     ...
;             float ls0 = 0.f, ls1 = 0.f;
;     ...
;             union PFU { u32x4 u; bf16x8 b; };
;             PFU p0, p1, p2, p3;
;             AT_EXP(s0, 0, p0);
; #pragma unroll
;             for (int kk = 0; kk < 2; ++kk)
; #pragma unroll
;                 for (int db = 0; db < NDB; ++db) vc[kk * NDB + db] = *(const ALAS bf16x8*)(sb + vx[kk + 2] + db * 4096);
;             __builtin_amdgcn_sched_barrier(0);
; #pragma unroll
;             for (int db = 0; db < NDB; ++db) o[db] = __builtin_amdgcn_mfma_f32_32x32x16_bf16(va[db], p0.b, o[db], 0, 0, 0);
;             AT_EXP(s0, 8, p1);
;             __builtin_amdgcn_sched_barrier(0);
; #pragma unroll
;             for (int db = 0; db < NDB; ++db) o[db] = __builtin_amdgcn_mfma_f32_32x32x16_bf16(va[NDB + db], p1.b, o[db], 0, 0, 0);
;             AT_EXP(s1, 0, p2);
;             __builtin_amdgcn_sched_barrier(0);
; #pragma unroll
;             for (int db = 0; db < NDB; ++db) o[db] = __builtin_amdgcn_mfma_f32_32x32x16_bf16(vc[db], p2.b, o[db], 0, 0, 0);
;             AT_EXP(s1, 8, p3);
;             __builtin_amdgcn_sched_barrier(0);
; #pragma unroll
;             for (int db = 0; db < NDB; ++db) o[db] = __builtin_amdgcn_mfma_f32_32x32x16_bf16(vc[NDB + db], p3.b, o[db], 0, 0, 0);
;             __builtin_amdgcn_sched_barrier(0);
;     ...
;             l_run += ls0 + ls1;
.LSPs_pure:
	v_lshl_add_u64 v[174:175], v[174:175], 0, s[60:61]
	v_lshl_add_u64 v[172:173], v[172:173], 0, s[48:49]
	s_add_i32 s98, s78, 0x10000
	s_and_b32 s98, s98, 0x18000
	s_add_i32 s98, s98, s29
	s_add_i32 s101, s78, 0x8000
	s_and_b32 s101, s101, 0x18000
	s_add_i32 s101, s101, s29
	v_lshl_add_u64 v[208:209], v[174:175], 0, s[40:41]
	v_lshl_add_u64 v[210:211], v[172:173], 0, s[40:41]
	s_add_i32 s80, s78, 0xffff8000
	s_and_b32 s80, s80, 0x18000
	v_add3_u32 v212, s80, v178, v162
	v_add3_u32 v213, s80, v180, v162
	v_add3_u32 v214, s80, v182, v162
	v_add3_u32 v215, s80, v184, v162
	s_add_i32 s99, s76, 64
	s_cmp_gt_u32 s99, s28
	s_cselect_b32 m0, s31, s30
	s_cmp_lt_u32 s99, s33
	s_cselect_b32 s65, 1, 0
	s_cmp_gt_i32 s99, s67
	s_cselect_b32 s65, s65, 0
	s_cmp_lg_u32 s65, 0
	s_cselect_b32 m0, 0, m0
	s_add_i32 s99, s78, 0xffff0000
	s_and_b32 s99, s99, 0x18000
	s_add_i32 s79, s79, 1
	s_add_i32 s78, s78, 0x8000
	s_addk_i32 s77, 0x100
	s_add_i32 s76, s76, 64
	v_exp_f32_e32 v98, v98
	v_exp_f32_e32 v99, v99
	v_exp_f32_e32 v100, v100
	v_exp_f32_e32 v101, v101
	v_exp_f32_e32 v102, v102
	v_exp_f32_e32 v103, v103
	v_exp_f32_e32 v104, v104
	v_exp_f32_e32 v105, v105
	v_cvt_pk_bf16_f32 v238, v98, v99
	v_cvt_pk_bf16_f32 v239, v100, v101
	v_cvt_pk_bf16_f32 v240, v102, v103
	v_cvt_pk_bf16_f32 v241, v104, v105
	v_mov_b32_e32 v228, v98
	v_mov_b32_e32 v229, v102
	v_add_f32_e32 v228, v228, v99
	v_add_f32_e32 v229, v229, v103
	v_add_f32_e32 v228, v228, v100
	v_add_f32_e32 v229, v229, v104
	v_add_f32_e32 v228, v228, v101
	v_add_f32_e32 v229, v229, v105
	v_exp_f32_e32 v106, v106
	v_exp_f32_e32 v107, v107
	v_exp_f32_e32 v108, v108
	v_exp_f32_e32 v109, v109
	v_exp_f32_e32 v110, v110
	v_exp_f32_e32 v111, v111
	v_exp_f32_e32 v112, v112
	v_exp_f32_e32 v113, v113
	v_cvt_pk_bf16_f32 v242, v106, v107
	v_cvt_pk_bf16_f32 v243, v108, v109
	v_cvt_pk_bf16_f32 v244, v110, v111
	v_cvt_pk_bf16_f32 v245, v112, v113
	v_add_f32_e32 v228, v228, v106
	v_add_f32_e32 v229, v229, v110
	v_add_f32_e32 v228, v228, v107
	v_add_f32_e32 v229, v229, v111
	v_add_f32_e32 v228, v228, v108
	v_add_f32_e32 v229, v229, v112
	v_add_f32_e32 v228, v228, v109
	v_add_f32_e32 v229, v229, v113
	v_exp_f32_e32 v82, v82
	v_exp_f32_e32 v83, v83
	v_exp_f32_e32 v84, v84
	v_exp_f32_e32 v85, v85
	v_exp_f32_e32 v86, v86
	v_exp_f32_e32 v87, v87
	v_exp_f32_e32 v88, v88
	v_exp_f32_e32 v89, v89
	v_cvt_pk_bf16_f32 v246, v82, v83
	v_cvt_pk_bf16_f32 v247, v84, v85
	v_cvt_pk_bf16_f32 v248, v86, v87
	v_cvt_pk_bf16_f32 v249, v88, v89
	v_add_f32_e32 v228, v228, v82
	v_add_f32_e32 v229, v229, v86
	v_add_f32_e32 v228, v228, v83
	v_add_f32_e32 v229, v229, v87
	v_add_f32_e32 v228, v228, v84
	v_add_f32_e32 v229, v229, v88
	v_add_f32_e32 v228, v228, v85
	v_add_f32_e32 v229, v229, v89
	v_exp_f32_e32 v90, v90
	v_exp_f32_e32 v91, v91
	v_exp_f32_e32 v92, v92
	v_exp_f32_e32 v93, v93
	v_exp_f32_e32 v94, v94
	v_exp_f32_e32 v95, v95
	v_exp_f32_e32 v96, v96
	v_exp_f32_e32 v97, v97
	v_cvt_pk_bf16_f32 v250, v90, v91
	v_cvt_pk_bf16_f32 v251, v92, v93
	v_cvt_pk_bf16_f32 v252, v94, v95
	v_cvt_pk_bf16_f32 v253, v96, v97
	v_add_f32_e32 v228, v228, v90
	v_add_f32_e32 v229, v229, v94
	v_add_f32_e32 v228, v228, v91
	v_add_f32_e32 v229, v229, v95
	v_add_f32_e32 v228, v228, v92
	v_add_f32_e32 v229, v229, v96
	v_add_f32_e32 v228, v228, v93
	v_add_f32_e32 v229, v229, v97
	ds_read_b128 v[130:133], v212
	ds_read_b128 v[134:137], v212 offset:4096
	ds_read_b128 v[138:141], v213
	ds_read_b128 v[142:145], v213 offset:4096
	ds_read_b128 v[146:149], v214
	ds_read_b128 v[150:153], v214 offset:4096
	ds_read_b128 v[158:161], v215
	ds_read_b128 v[204:207], v215 offset:4096
	v_add_f32_e32 v228, v228, v229
	v_cmp_nge_f32_e32 vcc, 0x53800000, v228
	s_cbranch_vccnz .LSPs_redo
	v_add_f32_e32 v0, v0, v228
	s_cmpk_eq_i32 s77, 0x2000
	s_cbranch_scc0 .LSPs_top
	s_branch .LSPs_exit
; #define ALAS __attribute__((address_space(3)))
; template <bool WIN> ...
;     ...
;             f32x16 s0, s1;
;             const ALAS unsigned char* sb = lds + (tr & (NSTG - 1)) * STAGE;
;             {
;                 bf16x8 ka[8];
; #pragma unroll
;                 for (int ds = 0; ds < 4; ++ds) { ka[2 * ds] = *(const ALAS bf16x8*)(sb + kx[ds]); ka[2 * ds + 1] = *(const ALAS bf16x8*)(sb + kx[ds] + 4096); }
;                 __builtin_amdgcn_sched_barrier(0);
;                 s0 = __builtin_amdgcn_mfma_f32_32x32x16_bf16(ka[0], qf(0), cvec, 0, 0, 0);
;                 s1 = __builtin_amdgcn_mfma_f32_32x32x16_bf16(ka[1], qf(0), cvec, 0, 0, 0);
; #pragma unroll
;                 for (int ds = 1; ds < 4; ++ds) {
;                     s0 = __builtin_amdgcn_mfma_f32_32x32x16_bf16(ka[2 * ds], qf(ds), s0, 0, 0, 0);
;                     s1 = __builtin_amdgcn_mfma_f32_32x32x16_bf16(ka[2 * ds + 1], qf(ds), s1, 0, 0, 0);
;                 }
;             }
;             bf16x8 va[2 * NDB], vc[2 * NDB];
; #pragma unroll
;             for (int kk = 0; kk < 2; ++kk)
; #pragma unroll
;                 for (int db = 0; db < NDB; ++db) va[kk * NDB + db] = *(const ALAS bf16x8*)(sb + vx[kk] + db * 4096);
;             __builtin_amdgcn_sched_barrier(0);
;             if (near) {
;                 const ALAS float* lb = lut + (k0 + 8 * hi - qabs + LUTC);
; #pragma unroll
;                 for (int r = 0; r < 16; ++r) { s0[r] += lb[16 * (r >> 3) + (r & 7)]; s1[r] += lb[32 + 16 * (r >> 3) + (r & 7)];
;                     if ((r & 7) == 7) __builtin_amdgcn_sched_barrier(0); }
;             }
.LSPs_redo:
	s_add_i32 s80, s78, 0xfffe8000
	s_and_b32 s80, s80, 0x18000
	v_add3_u32 v203, s80, v178, v162
	ds_read_b128 v[130:133], v203
	ds_read_b128 v[134:137], v203 offset:4096
	v_add3_u32 v203, s80, v180, v162
	ds_read_b128 v[138:141], v203
	ds_read_b128 v[142:145], v203 offset:4096
	v_add3_u32 v203, s80, v182, v162
	ds_read_b128 v[146:149], v203
	ds_read_b128 v[150:153], v203 offset:4096
	v_add3_u32 v203, s80, v184, v162
	ds_read_b128 v[158:161], v203
	ds_read_b128 v[204:207], v203 offset:4096
	s_waitcnt lgkmcnt(0)
	v_mfma_f32_32x32x16_bf16 v[98:113], v[130:133], v[126:129], v[66:81]
	v_mfma_f32_32x32x16_bf16 v[82:97], v[134:137], v[126:129], v[66:81]
	v_mfma_f32_32x32x16_bf16 v[98:113], v[138:141], v[122:125], v[98:113]
	v_mfma_f32_32x32x16_bf16 v[82:97], v[142:145], v[122:125], v[82:97]
	v_mfma_f32_32x32x16_bf16 v[98:113], v[146:149], v[118:121], v[98:113]
	v_mfma_f32_32x32x16_bf16 v[82:97], v[150:153], v[118:121], v[82:97]
	v_mfma_f32_32x32x16_bf16 v[98:113], v[158:161], v[114:117], v[98:113]
	v_mfma_f32_32x32x16_bf16 v[82:97], v[204:207], v[114:117], v[82:97]
	s_nop 7
	s_nop 7
	s_cmp_eq_u32 s64, 0
	s_cbranch_scc1 .LSPs_redomax
	s_addk_i32 s77, 0xff00
	v_add_u32_e32 v203, s77, v171
	v_add_u32_e32 v204, 0x23b80, v203
	v_add_u32_e32 v206, 0x23c00, v203
	v_add_u32_e32 v210, 0x23c08, v203
	v_add_u32_e32 v208, 0x23b88, v203
	v_add_u32_e32 v218, 0x23c10, v203
	v_add_u32_e32 v212, 0x23b90, v203
	v_add_u32_e32 v216, 0x23c18, v203
	v_add_u32_e32 v214, 0x23b98, v203
	ds_read2_b32 v[204:205], v204 offset1:1
	ds_read2_b32 v[206:207], v206 offset1:1
	ds_read2_b32 v[208:209], v208 offset1:1
	ds_read2_b32 v[210:211], v210 offset1:1
	ds_read2_b32 v[212:213], v212 offset1:1
	ds_read2_b32 v[214:215], v214 offset1:1
	ds_read2_b32 v[216:217], v216 offset1:1
	ds_read2_b32 v[218:219], v218 offset1:1
	v_add_u32_e32 v220, 0x23bc0, v203
	v_add_u32_e32 v222, 0x23c40, v203
	v_add_u32_e32 v226, 0x23c48, v203
	v_add_u32_e32 v224, 0x23bc8, v203
	v_add_u32_e32 v228, 0x23bd0, v203
	v_add_u32_e32 v234, 0x23c58, v203
	ds_read2_b32 v[220:221], v220 offset1:1
	ds_read2_b32 v[222:223], v222 offset1:1
	ds_read2_b32 v[224:225], v224 offset1:1
	ds_read2_b32 v[226:227], v226 offset1:1
	v_add_u32_e32 v231, 0x23c50, v203
	v_add_u32_e32 v203, 0x23bd8, v203
	ds_read2_b32 v[228:229], v228 offset1:1
	ds_read2_b32 v[232:233], v203 offset1:1
	ds_read2_b32 v[234:235], v234 offset1:1
	ds_read2_b32 v[236:237], v231 offset1:1
	s_waitcnt lgkmcnt(10)
	v_pk_add_f32 v[104:105], v[104:105], v[214:215]
	v_pk_add_f32 v[102:103], v[102:103], v[212:213]
	v_pk_add_f32 v[100:101], v[100:101], v[208:209]
	s_waitcnt lgkmcnt(2)
	v_pk_add_f32 v[112:113], v[112:113], v[232:233]
	v_pk_add_f32 v[110:111], v[110:111], v[228:229]
	v_pk_add_f32 v[108:109], v[108:109], v[224:225]
	v_pk_add_f32 v[106:107], v[106:107], v[220:221]
	v_pk_add_f32 v[98:99], v[98:99], v[204:205]
	v_pk_add_f32 v[88:89], v[88:89], v[216:217]
	v_pk_add_f32 v[86:87], v[86:87], v[218:219]
	v_pk_add_f32 v[84:85], v[84:85], v[210:211]
	s_waitcnt lgkmcnt(1)
	v_pk_add_f32 v[96:97], v[96:97], v[234:235]
	s_waitcnt lgkmcnt(0)
	v_pk_add_f32 v[94:95], v[94:95], v[236:237]
	v_pk_add_f32 v[92:93], v[92:93], v[226:227]
	v_pk_add_f32 v[90:91], v[90:91], v[222:223]
	v_pk_add_f32 v[82:83], v[82:83], v[206:207]
	s_addk_i32 s77, 0x100

; #define ALAS __attribute__((address_space(3)))
; template <bool WIN> ...
;     ...
;             float ls0 = 0.f, ls1 = 0.f;
;     ...
;             union PFU { u32x4 u; bf16x8 b; };
;             PFU p0, p1, p2, p3;
;             AT_EXP(s0, 0, p0);
; #pragma unroll
;             for (int kk = 0; kk < 2; ++kk)
; #pragma unroll
;                 for (int db = 0; db < NDB; ++db) vc[kk * NDB + db] = *(const ALAS bf16x8*)(sb + vx[kk + 2] + db * 4096);
;             __builtin_amdgcn_sched_barrier(0);
; #pragma unroll
;             for (int db = 0; db < NDB; ++db) o[db] = __builtin_amdgcn_mfma_f32_32x32x16_bf16(va[db], p0.b, o[db], 0, 0, 0);
;             AT_EXP(s0, 8, p1);
;             __builtin_amdgcn_sched_barrier(0);
; #pragma unroll
;             for (int db = 0; db < NDB; ++db) o[db] = __builtin_amdgcn_mfma_f32_32x32x16_bf16(va[NDB + db], p1.b, o[db], 0, 0, 0);
;             AT_EXP(s1, 0, p2);
;             __builtin_amdgcn_sched_barrier(0);
; #pragma unroll
;             for (int db = 0; db < NDB; ++db) o[db] = __builtin_amdgcn_mfma_f32_32x32x16_bf16(vc[db], p2.b, o[db], 0, 0, 0);
;             AT_EXP(s1, 8, p3);
;             __builtin_amdgcn_sched_barrier(0);
; #pragma unroll
;             for (int db = 0; db < NDB; ++db) o[db] = __builtin_amdgcn_mfma_f32_32x32x16_bf16(vc[NDB + db], p3.b, o[db], 0, 0, 0);
;             __builtin_amdgcn_sched_barrier(0);
;     ...
;             l_run += ls0 + ls1;
.LSPs_pure2:
	s_add_i32 s80, s78, 0xffff0000
	s_and_b32 s80, s80, 0x18000
	v_lshl_add_u64 v[208:209], v[174:175], 0, s[40:41]
	v_lshl_add_u64 v[210:211], v[172:173], 0, s[40:41]
	v_add3_u32 v212, s80, v178, v162
	v_add3_u32 v213, s80, v180, v162
	v_add3_u32 v214, s80, v182, v162
	v_add3_u32 v215, s80, v184, v162
	v_exp_f32_e32 v98, v98
	v_exp_f32_e32 v99, v99
	v_exp_f32_e32 v100, v100
	v_exp_f32_e32 v101, v101
	v_exp_f32_e32 v102, v102
	v_exp_f32_e32 v103, v103
	v_exp_f32_e32 v104, v104
	v_exp_f32_e32 v105, v105
	v_cvt_pk_bf16_f32 v238, v98, v99
	v_cvt_pk_bf16_f32 v239, v100, v101
	v_cvt_pk_bf16_f32 v240, v102, v103
	v_cvt_pk_bf16_f32 v241, v104, v105
	v_mov_b32_e32 v228, v98
	v_mov_b32_e32 v229, v102
	v_add_f32_e32 v228, v228, v99
	v_add_f32_e32 v229, v229, v103
	v_add_f32_e32 v228, v228, v100
	v_add_f32_e32 v229, v229, v104
	v_add_f32_e32 v228, v228, v101
	v_add_f32_e32 v229, v229, v105
	v_exp_f32_e32 v106, v106
	v_exp_f32_e32 v107, v107
	v_exp_f32_e32 v108, v108
	v_exp_f32_e32 v109, v109
	v_exp_f32_e32 v110, v110
	v_exp_f32_e32 v111, v111
	v_exp_f32_e32 v112, v112
	v_exp_f32_e32 v113, v113
	v_cvt_pk_bf16_f32 v242, v106, v107
	v_cvt_pk_bf16_f32 v243, v108, v109
	v_cvt_pk_bf16_f32 v244, v110, v111
	v_cvt_pk_bf16_f32 v245, v112, v113
	v_add_f32_e32 v228, v228, v106
	v_add_f32_e32 v229, v229, v110
	v_add_f32_e32 v228, v228, v107
	v_add_f32_e32 v229, v229, v111
	v_add_f32_e32 v228, v228, v108
	v_add_f32_e32 v229, v229, v112
	v_add_f32_e32 v228, v228, v109
	v_add_f32_e32 v229, v229, v113
	v_exp_f32_e32 v82, v82
	v_exp_f32_e32 v83, v83
	v_exp_f32_e32 v84, v84
	v_exp_f32_e32 v85, v85
	v_exp_f32_e32 v86, v86
	v_exp_f32_e32 v87, v87
	v_exp_f32_e32 v88, v88
	v_exp_f32_e32 v89, v89
	v_cvt_pk_bf16_f32 v246, v82, v83
	v_cvt_pk_bf16_f32 v247, v84, v85
	v_cvt_pk_bf16_f32 v248, v86, v87
	v_cvt_pk_bf16_f32 v249, v88, v89
	v_add_f32_e32 v228, v228, v82
	v_add_f32_e32 v229, v229, v86
	v_add_f32_e32 v228, v228, v83
	v_add_f32_e32 v229, v229, v87
	v_add_f32_e32 v228, v228, v84
	v_add_f32_e32 v229, v229, v88
	v_add_f32_e32 v228, v228, v85
	v_add_f32_e32 v229, v229, v89
	v_exp_f32_e32 v90, v90
	v_exp_f32_e32 v91, v91
	v_exp_f32_e32 v92, v92
	v_exp_f32_e32 v93, v93
	v_exp_f32_e32 v94, v94
	v_exp_f32_e32 v95, v95
	v_exp_f32_e32 v96, v96
	v_exp_f32_e32 v97, v97
	v_cvt_pk_bf16_f32 v250, v90, v91
	v_cvt_pk_bf16_f32 v251, v92, v93
	v_cvt_pk_bf16_f32 v252, v94, v95
	v_cvt_pk_bf16_f32 v253, v96, v97
	v_add_f32_e32 v228, v228, v90
	v_add_f32_e32 v229, v229, v94
	v_add_f32_e32 v228, v228, v91
	v_add_f32_e32 v229, v229, v95
	v_add_f32_e32 v228, v228, v92
	v_add_f32_e32 v229, v229, v96
	v_add_f32_e32 v228, v228, v93
	v_add_f32_e32 v229, v229, v97
	ds_read_b128 v[130:133], v212
	ds_read_b128 v[134:137], v212 offset:4096
	ds_read_b128 v[138:141], v213
	ds_read_b128 v[142:145], v213 offset:4096
	ds_read_b128 v[146:149], v214
	ds_read_b128 v[150:153], v214 offset:4096
	ds_read_b128 v[158:161], v215
	ds_read_b128 v[204:207], v215 offset:4096
	v_add_f32_e32 v228, v228, v229
	v_add_f32_e32 v0, v0, v228
	s_cmpk_eq_i32 s77, 0x2000
	s_cbranch_scc0 .LSPs_top
	s_branch .LSPs_exit
